# exchange poll without s_sleep between attempts (one sc1 round trip per attempt, bounded)
# speedup vs baseline: 1.0121x; 1.0014x over previous
;     __device__ __forceinline__ void run(const f32x4 (&v)[2][2][4][2], const Unit& u, int wr, int wc, int fr, int fq, PG8_LAS unsigned char* lds, int wid, int lane) const {
;     ...
;         if (wid == 0) {
;             unsigned sp = 0;
;             while ((unsigned)__builtin_amdgcn_readfirstlane(__hip_atomic_load(cnt + 64 * pmg, __ATOMIC_RELAXED, __HIP_MEMORY_SCOPE_AGENT)) < 32u) { __builtin_amdgcn_s_sleep(2); if (++sp > (1u << 22)) break; }
;             __builtin_amdgcn_fence(__ATOMIC_ACQUIRE, "agent");
;         }
;         asm volatile("s_waitcnt vmcnt(0) lgkmcnt(0)" ::: "memory"); __builtin_amdgcn_s_barrier(); asm volatile("" ::: "memory");
;         if (lane < 32) {
;             const float* slot = xbuf + (size_t)(pmg * BM + row) * 4; float t = 0.f;
; #pragma unroll
;             for (int k = 0; k < 4; ++k) t += __hip_atomic_load(slot + k, __ATOMIC_RELAXED, __HIP_MEMORY_SCOPE_AGENT);
;             S[row] = rsqrtf(t * (1.0f / 1024.0f) + eps);
.Lpss_a0_poll:
	global_load_dwordx4 v[128:131], v[204:205], off offset:0 sc1
	global_load_dwordx4 v[132:135], v[204:205], off offset:1024 sc1
	s_waitcnt vmcnt(0)
	v_min3_f32 v207, v128, v129, v130
	v_min3_f32 v207, v207, v131, v132
	v_min3_f32 v207, v207, v133, v134
	v_min_f32_e32 v207, v207, v135
	v_cmp_gt_f32_e32 vcc, 0, v207
	s_cbranch_vccz .Lpss_a0_ok
	s_sub_u32 s26, s26, 1
	s_cmp_lg_u32 s26, 0
	s_cbranch_scc1 .Lpss_a0_poll

;     __device__ __forceinline__ void run(const f32x4 (&v)[2][2][4][2], const Unit& u, int wr, int wc, int fr, int fq, PG8_LAS unsigned char* lds, int wid, int lane) const {
;     ...
;         if (wid == 0) {
;             unsigned sp = 0;
;             while ((unsigned)__builtin_amdgcn_readfirstlane(__hip_atomic_load(cnt + 64 * pmg, __ATOMIC_RELAXED, __HIP_MEMORY_SCOPE_AGENT)) < 32u) { __builtin_amdgcn_s_sleep(2); if (++sp > (1u << 22)) break; }
;             __builtin_amdgcn_fence(__ATOMIC_ACQUIRE, "agent");
;         }
;         asm volatile("s_waitcnt vmcnt(0) lgkmcnt(0)" ::: "memory"); __builtin_amdgcn_s_barrier(); asm volatile("" ::: "memory");
;         if (lane < 32) {
;             const float* slot = xbuf + (size_t)(pmg * BM + row) * 4; float t = 0.f;
; #pragma unroll
;             for (int k = 0; k < 4; ++k) t += __hip_atomic_load(slot + k, __ATOMIC_RELAXED, __HIP_MEMORY_SCOPE_AGENT);
;             S[row] = rsqrtf(t * (1.0f / 1024.0f) + eps);
.Lpss_a1_poll:
	global_load_dwordx4 v[128:131], v[204:205], off offset:2048 sc1
	global_load_dwordx4 v[132:135], v[204:205], off offset:3072 sc1
	s_waitcnt vmcnt(0)
	v_min3_f32 v207, v128, v129, v130
	v_min3_f32 v207, v207, v131, v132
	v_min3_f32 v207, v207, v133, v134
	v_min_f32_e32 v207, v207, v135
	v_cmp_gt_f32_e32 vcc, 0, v207
	s_cbranch_vccz .Lpss_a1_ok
	s_sub_u32 s26, s26, 1
	s_cmp_lg_u32 s26, 0
	s_cbranch_scc1 .Lpss_a1_poll

;     __device__ __forceinline__ void run(const f32x4 (&v)[2][2][4][2], const Unit& u, int wr, int wc, int fr, int fq, PG8_LAS unsigned char* lds, int wid, int lane) const {
;     ...
;         if (wid == 0) {
;             unsigned sp = 0;
;             while ((unsigned)__builtin_amdgcn_readfirstlane(__hip_atomic_load(cnt + 64 * pmg, __ATOMIC_RELAXED, __HIP_MEMORY_SCOPE_AGENT)) < 32u) { __builtin_amdgcn_s_sleep(2); if (++sp > (1u << 22)) break; }
;             __builtin_amdgcn_fence(__ATOMIC_ACQUIRE, "agent");
;         }
;         asm volatile("s_waitcnt vmcnt(0) lgkmcnt(0)" ::: "memory"); __builtin_amdgcn_s_barrier(); asm volatile("" ::: "memory");
;         if (lane < 32) {
;             const float* slot = xbuf + (size_t)(pmg * BM + row) * 4; float t = 0.f;
; #pragma unroll
;             for (int k = 0; k < 4; ++k) t += __hip_atomic_load(slot + k, __ATOMIC_RELAXED, __HIP_MEMORY_SCOPE_AGENT);
;             S[row] = rsqrtf(t * (1.0f / 1024.0f) + eps);
.Lpss_b0_poll:
	global_load_dwordx4 v[128:131], v[204:205], off offset:0 sc1
	global_load_dwordx4 v[132:135], v[204:205], off offset:1024 sc1
	s_waitcnt vmcnt(0)
	v_min3_f32 v207, v128, v129, v130
	v_min3_f32 v207, v207, v131, v132
	v_min3_f32 v207, v207, v133, v134
	v_min_f32_e32 v207, v207, v135
	v_cmp_gt_f32_e32 vcc, 0, v207
	s_cbranch_vccz .Lpss_b0_ok
	s_sub_u32 s18, s18, 1
	s_cmp_lg_u32 s18, 0
	s_cbranch_scc1 .Lpss_b0_poll

;     __device__ __forceinline__ void run(const f32x4 (&v)[2][2][4][2], const Unit& u, int wr, int wc, int fr, int fq, PG8_LAS unsigned char* lds, int wid, int lane) const {
;     ...
;         if (wid == 0) {
;             unsigned sp = 0;
;             while ((unsigned)__builtin_amdgcn_readfirstlane(__hip_atomic_load(cnt + 64 * pmg, __ATOMIC_RELAXED, __HIP_MEMORY_SCOPE_AGENT)) < 32u) { __builtin_amdgcn_s_sleep(2); if (++sp > (1u << 22)) break; }
;             __builtin_amdgcn_fence(__ATOMIC_ACQUIRE, "agent");
;         }
;         asm volatile("s_waitcnt vmcnt(0) lgkmcnt(0)" ::: "memory"); __builtin_amdgcn_s_barrier(); asm volatile("" ::: "memory");
;         if (lane < 32) {
;             const float* slot = xbuf + (size_t)(pmg * BM + row) * 4; float t = 0.f;
; #pragma unroll
;             for (int k = 0; k < 4; ++k) t += __hip_atomic_load(slot + k, __ATOMIC_RELAXED, __HIP_MEMORY_SCOPE_AGENT);
;             S[row] = rsqrtf(t * (1.0f / 1024.0f) + eps);
.Lpss_b1_poll:
	global_load_dwordx4 v[128:131], v[204:205], off offset:2048 sc1
	global_load_dwordx4 v[132:135], v[204:205], off offset:3072 sc1
	s_waitcnt vmcnt(0)
	v_min3_f32 v207, v128, v129, v130
	v_min3_f32 v207, v207, v131, v132
	v_min3_f32 v207, v207, v133, v134
	v_min_f32_e32 v207, v207, v135
	v_cmp_gt_f32_e32 vcc, 0, v207
	s_cbranch_vccz .Lpss_b1_ok
	s_sub_u32 s18, s18, 1
	s_cmp_lg_u32 s18, 0
	s_cbranch_scc1 .Lpss_b1_poll

;     __device__ __forceinline__ void run(const f32x4 (&v)[2][2][4][2], const Unit& u, int wr, int wc, int fr, int fq, PG8_LAS unsigned char* lds, int wid, int lane) const {
;     ...
;         if (wid == 0) {
;             unsigned sp = 0;
;             while ((unsigned)__builtin_amdgcn_readfirstlane(__hip_atomic_load(cnt + 64 * pmg, __ATOMIC_RELAXED, __HIP_MEMORY_SCOPE_AGENT)) < 32u) { __builtin_amdgcn_s_sleep(2); if (++sp > (1u << 22)) break; }
;             __builtin_amdgcn_fence(__ATOMIC_ACQUIRE, "agent");
;         }
;         asm volatile("s_waitcnt vmcnt(0) lgkmcnt(0)" ::: "memory"); __builtin_amdgcn_s_barrier(); asm volatile("" ::: "memory");
;         if (lane < 32) {
;             const float* slot = xbuf + (size_t)(pmg * BM + row) * 4; float t = 0.f;
; #pragma unroll
;             for (int k = 0; k < 4; ++k) t += __hip_atomic_load(slot + k, __ATOMIC_RELAXED, __HIP_MEMORY_SCOPE_AGENT);
;             S[row] = rsqrtf(t * (1.0f / 1024.0f) + eps);
.Lpss_c0_poll:
	global_load_dwordx4 v[128:131], v[136:137], off offset:0 sc1
	global_load_dwordx4 v[132:135], v[136:137], off offset:1024 sc1
	s_waitcnt vmcnt(0)
	v_min3_f32 v191, v128, v129, v130
	v_min3_f32 v191, v191, v131, v132
	v_min3_f32 v191, v191, v133, v134
	v_min_f32_e32 v191, v191, v135
	v_cmp_gt_f32_e32 vcc, 0, v191
	s_cbranch_vccz .Lpss_c0_ok
	s_sub_u32 s25, s25, 1
	s_cmp_lg_u32 s25, 0
	s_cbranch_scc1 .Lpss_c0_poll

;     __device__ __forceinline__ void run(const f32x4 (&v)[2][2][4][2], const Unit& u, int wr, int wc, int fr, int fq, PG8_LAS unsigned char* lds, int wid, int lane) const {
;     ...
;         if (wid == 0) {
;             unsigned sp = 0;
;             while ((unsigned)__builtin_amdgcn_readfirstlane(__hip_atomic_load(cnt + 64 * pmg, __ATOMIC_RELAXED, __HIP_MEMORY_SCOPE_AGENT)) < 32u) { __builtin_amdgcn_s_sleep(2); if (++sp > (1u << 22)) break; }
;             __builtin_amdgcn_fence(__ATOMIC_ACQUIRE, "agent");
;         }
;         asm volatile("s_waitcnt vmcnt(0) lgkmcnt(0)" ::: "memory"); __builtin_amdgcn_s_barrier(); asm volatile("" ::: "memory");
;         if (lane < 32) {
;             const float* slot = xbuf + (size_t)(pmg * BM + row) * 4; float t = 0.f;
; #pragma unroll
;             for (int k = 0; k < 4; ++k) t += __hip_atomic_load(slot + k, __ATOMIC_RELAXED, __HIP_MEMORY_SCOPE_AGENT);
;             S[row] = rsqrtf(t * (1.0f / 1024.0f) + eps);
.Lpss_c1_poll:
	global_load_dwordx4 v[128:131], v[136:137], off offset:2048 sc1
	global_load_dwordx4 v[132:135], v[136:137], off offset:3072 sc1
	s_waitcnt vmcnt(0)
	v_min3_f32 v191, v128, v129, v130
	v_min3_f32 v191, v191, v131, v132
	v_min3_f32 v191, v191, v133, v134
	v_min_f32_e32 v191, v191, v135
	v_cmp_gt_f32_e32 vcc, 0, v191
	s_cbranch_vccz .Lpss_c1_ok
	s_sub_u32 s25, s25, 1
	s_cmp_lg_u32 s25, 0
	s_cbranch_scc1 .Lpss_c1_poll
